# stack32 + handshake trims: seam-5 arrival as a returning atomic (passes at once when it completes the panel), no s_sleep in the dataflow poll loops
# baseline (speedup 1.0000x reference)
.Ldf3_l:
	global_load_dword v4, v2, s[76:77] sc1
	s_waitcnt vmcnt(0)
	v_readfirstlane_b32 s0, v4
	s_cmp_ge_u32 s0, 16
	s_cbranch_scc1 .Ldf3_g
	s_add_i32 s101, s101, 1
	s_cmp_lt_u32 s101, 0x100000
	s_cbranch_scc1 .Ldf3_l

.Ldf4p_l:
	global_load_dword v6, v5, s[76:77] sc1
	s_waitcnt vmcnt(0)
	v_readfirstlane_b32 s99, v6
	s_cmp_ge_u32 s99, s100
	s_cbranch_scc1 .Ldf4p_g
	s_add_i32 s101, s101, 1
	s_cmp_lt_u32 s101, 0x100000
	s_cbranch_scc1 .Ldf4p_l

.Ldf4_l:
	global_load_dword v4, v2, s[76:77] sc1
	global_load_dword v6, v5, s[76:77] sc1
	s_waitcnt vmcnt(0)
	v_readfirstlane_b32 s0, v4
	v_readfirstlane_b32 s1, v6
	s_cmp_ge_u32 s0, 16
	s_cselect_b32 s0, 1, 0
	s_cmp_ge_u32 s1, s100
	s_cselect_b32 s1, 1, 0
	s_and_b32 s0, s0, s1
	s_cmp_lg_u32 s0, 0
	s_cbranch_scc1 .Ldf4_g
	s_add_i32 s101, s101, 1
	s_cmp_lt_u32 s101, 0x100000
	s_cbranch_scc1 .Ldf4_l

.LBB0_832:
	s_waitcnt vmcnt(0)
	s_barrier
	s_and_saveexec_b64 s[6:7], s[84:85]
	s_cbranch_execz .LBB0_886
	s_cmp_lg_u32 s79, 0x100
	s_cbranch_scc1 .Ldf5_full
	s_and_b32 s0, s78, 7
	s_lshl_b32 s0, s0, 5
	s_lshr_b32 s1, s78, 3
	s_add_i32 s0, s0, s1
	s_lshr_b32 s1, s0, 6
	s_lshl_b32 s1, s1, 3
	s_and_b32 s98, s0, 7
	s_add_i32 s98, s98, s1
	s_lshl_b32 s98, s98, 8
	s_add_i32 s98, s98, 0xc000
	v_mov_b32_e32 v2, s98
	v_mov_b32_e32 v3, 1
	global_atomic_add v4, v2, v3, s[76:77] sc0
	s_waitcnt vmcnt(0)
	v_readfirstlane_b32 s0, v4
	s_cmp_ge_u32 s0, 7
	s_cbranch_scc1 .Ldf5_go
	s_mov_b32 s99, 0
.Ldf5_poll:
	global_load_dword v4, v2, s[76:77] sc1
	s_waitcnt vmcnt(0)
	v_readfirstlane_b32 s0, v4
	s_cmp_ge_u32 s0, 8
	s_cbranch_scc1 .Ldf5_go
	s_add_i32 s99, s99, 1
	s_cmp_lt_u32 s99, 0x100000
	s_cbranch_scc1 .Ldf5_poll
